# inline-asm s_nop pads before QK/PV MFMAs removed in the MLA loop (24, even byte shift)
# speedup vs baseline: 1.0066x; 1.0014x over previous
.LBB2_333:
	v_lshl_add_u64 v[170:171], s[12:13], 0, v[164:165]
	s_mov_b64 s[0:1], 0xd090000
	v_lshl_add_u64 v[66:67], v[170:171], 0, s[0:1]
	s_mul_i32 s0, s63, 0x6000
	s_add_i32 s2, s61, s0
	s_mov_b32 m0, s2
	s_mov_b64 s[0:1], 0xd090080
	global_load_lds_dwordx4 v[66:67], off
	v_lshl_add_u64 v[66:67], v[170:171], 0, s[0:1]
	s_add_i32 m0, s2, 0x2000
	s_mov_b64 s[0:1], 0xd090100
	global_load_lds_dwordx4 v[66:67], off
	v_lshl_add_u64 v[66:67], v[170:171], 0, s[0:1]
	s_add_i32 m0, s2, 0x4000
	v_lshl_add_u64 v[168:169], s[12:13], 0, v[166:167]
	s_mov_b64 s[0:1], 0xe840000
	global_load_lds_dwordx4 v[66:67], off
	v_lshl_add_u64 v[66:67], v[168:169], 0, s[0:1]
	s_lshl_b32 s0, s24, 14
	s_add_i32 s2, s62, s0
	s_mov_b32 m0, s2
	s_mov_b64 s[0:1], 0xe850000
	global_load_lds_dwordx4 v[66:67], off
	v_lshl_add_u64 v[66:67], v[168:169], 0, s[0:1]
	s_add_i32 m0, s2, 0x2000
	s_nop 0
	global_load_lds_dwordx4 v[66:67], off
	s_mul_i32 s0, s64, 0x6000
	s_add_i32 s0, s0, 0
	v_add_u32_e32 v0, s0, v197
	v_add_u32_e32 v156, s0, v198
	v_add_u32_e32 v157, s0, v199
	ds_read_b128 v[66:69], v0 offset:0
	ds_read_b128 v[70:73], v0 offset:0x1000
	ds_read_b128 v[220:223], v156 offset:0
	ds_read_b128 v[224:227], v156 offset:0x1000
	ds_read_b128 v[228:231], v157 offset:0
	ds_read_b128 v[232:235], v157 offset:0x1000
	v_add_u32_e32 v158, s0, v200
	s_setprio 1
	s_waitcnt lgkmcnt(4)
	ds_read_b128 v[236:239], v158 offset:0
	ds_read_b128 v[240:243], v158 offset:0x1000
	s_waitcnt lgkmcnt(4)
	s_nop 0
	v_mfma_f32_32x32x16_bf16 v[82:97], v[66:69], v[142:145], 0
	v_mfma_f32_32x32x16_bf16 v[66:81], v[70:73], v[142:145], 0
	v_mfma_f32_32x32x16_bf16 v[82:97], v[220:223], v[138:141], v[82:97]
	ds_read_b128 v[220:223], v0 offset:0x2000
	v_mfma_f32_32x32x16_bf16 v[66:81], v[224:227], v[138:141], v[66:81]
	ds_read_b128 v[224:227], v0 offset:0x3000
	s_waitcnt lgkmcnt(4)
	v_mfma_f32_32x32x16_bf16 v[82:97], v[228:231], v[134:137], v[82:97]
	ds_read_b128 v[228:231], v156 offset:0x2000
	v_mfma_f32_32x32x16_bf16 v[66:81], v[232:235], v[134:137], v[66:81]
	ds_read_b128 v[232:235], v156 offset:0x3000
	s_waitcnt lgkmcnt(4)
	v_mfma_f32_32x32x16_bf16 v[82:97], v[236:239], v[130:133], v[82:97]
	ds_read_b128 v[236:239], v157 offset:0x2000
	v_mfma_f32_32x32x16_bf16 v[66:81], v[240:243], v[130:133], v[66:81]
	ds_read_b128 v[240:243], v157 offset:0x3000
	s_waitcnt lgkmcnt(4)
	v_mfma_f32_32x32x16_bf16 v[82:97], v[220:223], v[126:129], v[82:97]
	ds_read_b128 v[220:223], v158 offset:0x2000
	v_mfma_f32_32x32x16_bf16 v[66:81], v[224:227], v[126:129], v[66:81]
	ds_read_b128 v[224:227], v158 offset:0x3000
	s_waitcnt lgkmcnt(4)
	v_mfma_f32_32x32x16_bf16 v[82:97], v[228:231], v[122:125], v[82:97]
	ds_read_b128 v[228:231], v0 offset:0x4000
	v_mfma_f32_32x32x16_bf16 v[66:81], v[232:235], v[122:125], v[66:81]
	ds_read_b128 v[232:235], v0 offset:0x5000
	s_waitcnt lgkmcnt(4)
	v_mfma_f32_32x32x16_bf16 v[82:97], v[236:239], v[118:121], v[82:97]
	ds_read_b128 v[236:239], v156 offset:0x4000
	v_mfma_f32_32x32x16_bf16 v[66:81], v[240:243], v[118:121], v[66:81]
	ds_read_b128 v[240:243], v156 offset:0x5000
	s_waitcnt lgkmcnt(4)
	v_mfma_f32_32x32x16_bf16 v[82:97], v[220:223], v[114:117], v[82:97]
	ds_read_b128 v[220:223], v157 offset:0x4000
	v_mfma_f32_32x32x16_bf16 v[66:81], v[224:227], v[114:117], v[66:81]
	ds_read_b128 v[224:227], v157 offset:0x5000
	s_waitcnt lgkmcnt(4)
	v_mfma_f32_32x32x16_bf16 v[82:97], v[228:231], v[110:113], v[82:97]
	ds_read_b128 v[228:231], v158 offset:0x4000
	v_mfma_f32_32x32x16_bf16 v[66:81], v[232:235], v[110:113], v[66:81]
	ds_read_b128 v[232:235], v158 offset:0x5000
	s_waitcnt lgkmcnt(4)
	s_waitcnt lgkmcnt(2)
	s_nop 0
	s_waitcnt lgkmcnt(0)
	v_mfma_f32_32x32x16_bf16 v[82:97], v[236:239], v[106:109], v[82:97]
	v_mfma_f32_32x32x16_bf16 v[66:81], v[240:243], v[106:109], v[66:81]
	v_mfma_f32_32x32x16_bf16 v[82:97], v[220:223], v[102:105], v[82:97]
	v_mfma_f32_32x32x16_bf16 v[66:81], v[224:227], v[102:105], v[66:81]
	v_mfma_f32_32x32x16_bf16 v[82:97], v[228:231], v[98:101], v[82:97]
	v_mfma_f32_32x32x16_bf16 v[66:81], v[232:235], v[98:101], v[66:81]
	s_setprio 0
	v_exp_f32_e32 v224, v172
	v_add_f32_e32 v172, 0, v216
	v_add_f32_e32 v172, v218, v172
	v_add_f32_e32 v172, v214, v172
	v_add_f32_e32 v172, v217, v172
	v_add_f32_e32 v172, v212, v172
	v_add_f32_e32 v172, v215, v172
	v_add_f32_e32 v172, v211, v172
	v_add_f32_e32 v172, v213, v172
	v_add_f32_e32 v172, v208, v172
	v_add_f32_e32 v172, v210, v172
	v_add_f32_e32 v172, v206, v172
	v_add_f32_e32 v172, v209, v172
	v_exp_f32_e32 v0, v186
	v_add_f32_e32 v172, v204, v172
	v_exp_f32_e32 v156, v187
	v_add_f32_e32 v172, v207, v172
	v_exp_f32_e32 v157, v184
	v_add_f32_e32 v172, v203, v172
	v_exp_f32_e32 v158, v185
	v_add_f32_e32 v172, v205, v172
	v_exp_f32_e32 v159, v182
	v_add_f32_e32 v172, v0, v172
	v_exp_f32_e32 v184, v183
	v_add_f32_e32 v172, v156, v172
	v_exp_f32_e32 v185, v180
	v_add_f32_e32 v172, v157, v172
	v_exp_f32_e32 v186, v181
	v_add_f32_e32 v172, v158, v172
	v_exp_f32_e32 v187, v178
	v_add_f32_e32 v172, v159, v172
	v_exp_f32_e32 v219, v179
	v_add_f32_e32 v172, v184, v172
	v_exp_f32_e32 v220, v176
	v_add_f32_e32 v172, v185, v172
	v_exp_f32_e32 v221, v177
	v_add_f32_e32 v172, v186, v172
	v_exp_f32_e32 v222, v174
	v_add_f32_e32 v172, v187, v172
	v_exp_f32_e32 v223, v175
	v_add_f32_e32 v172, v219, v172
	v_add_f32_e32 v172, v220, v172
	v_exp_f32_e32 v225, v173
	v_add_f32_e32 v172, v221, v172
	v_add_f32_e32 v172, v222, v172
	v_add_f32_e32 v172, v223, v172
	v_add_f32_e32 v172, v224, v172
	v_add_f32_e32 v172, v225, v172
	v_mov_b32_e32 v173, v172
	v_cvt_pk_bf16_f32 v174, v216, v218
	v_cvt_pk_bf16_f32 v175, v214, v217
	v_cvt_pk_bf16_f32 v176, v212, v215
	s_nop 1
	v_permlane32_swap_b32_e32 v172, v173
	v_cvt_pk_bf16_f32 v177, v211, v213
	v_permlane32_swap_b32_e32 v174, v176
	v_cvt_pk_bf16_f32 v178, v208, v210
	v_cvt_pk_bf16_f32 v179, v206, v209
	v_cvt_pk_bf16_f32 v180, v204, v207
	v_cvt_pk_bf16_f32 v181, v203, v205
	v_cvt_pk_bf16_f32 v182, v0, v156
	v_cvt_pk_bf16_f32 v183, v157, v158
	v_cvt_pk_bf16_f32 v184, v159, v184
	v_cvt_pk_bf16_f32 v185, v185, v186
	v_cvt_pk_bf16_f32 v204, v187, v219
	v_cvt_pk_bf16_f32 v205, v220, v221
	v_cvt_pk_bf16_f32 v206, v222, v223
	v_cvt_pk_bf16_f32 v207, v224, v225
	v_permlane32_swap_b32_e32 v175, v177
	v_permlane32_swap_b32_e32 v178, v180
	v_permlane32_swap_b32_e32 v179, v181
	v_permlane32_swap_b32_e32 v182, v184
	v_permlane32_swap_b32_e32 v183, v185
	v_permlane32_swap_b32_e32 v204, v206
	v_permlane32_swap_b32_e32 v205, v207
	v_lshl_add_u32 v0, s40, 14, v196
	ds_read_b64_tr_b16 v[208:209], v0 offset:0
	ds_read_b64_tr_b16 v[210:211], v0 offset:0x800
	ds_read_b64_tr_b16 v[212:213], v0 offset:0x1000
	ds_read_b64_tr_b16 v[214:215], v0 offset:0x1800
	ds_read_b64_tr_b16 v[216:217], v0 offset:0x2000
	ds_read_b64_tr_b16 v[218:219], v0 offset:0x2800
	ds_read_b64_tr_b16 v[220:221], v0 offset:0x3000
	ds_read_b64_tr_b16 v[222:223], v0 offset:0x3800
	s_waitcnt lgkmcnt(0)
	s_nop 0
	v_mfma_f32_32x32x16_bf16 v[2:17], v[174:177], v[208:211], v[2:17]
	ds_read_b64_tr_b16 v[208:209], v0 offset:0x200
	ds_read_b64_tr_b16 v[210:211], v0 offset:0xa00
	v_mfma_f32_32x32x16_bf16 v[2:17], v[178:181], v[212:215], v[2:17]
	ds_read_b64_tr_b16 v[212:213], v0 offset:0x1200
	ds_read_b64_tr_b16 v[214:215], v0 offset:0x1a00
	v_mfma_f32_32x32x16_bf16 v[2:17], v[182:185], v[216:219], v[2:17]
	ds_read_b64_tr_b16 v[216:217], v0 offset:0x2200
	ds_read_b64_tr_b16 v[218:219], v0 offset:0x2a00
	v_mfma_f32_32x32x16_bf16 v[2:17], v[204:207], v[220:223], v[2:17]
	ds_read_b64_tr_b16 v[220:221], v0 offset:0x3200
	ds_read_b64_tr_b16 v[222:223], v0 offset:0x3a00
	s_waitcnt lgkmcnt(0)
	v_mfma_f32_32x32x16_bf16 v[50:65], v[174:177], v[208:211], v[50:65]
	ds_read_b64_tr_b16 v[208:209], v0 offset:0x400
	ds_read_b64_tr_b16 v[210:211], v0 offset:0xc00
	v_mfma_f32_32x32x16_bf16 v[50:65], v[178:181], v[212:215], v[50:65]
	ds_read_b64_tr_b16 v[212:213], v0 offset:0x1400
	ds_read_b64_tr_b16 v[214:215], v0 offset:0x1c00
	v_mfma_f32_32x32x16_bf16 v[50:65], v[182:185], v[216:219], v[50:65]
	ds_read_b64_tr_b16 v[216:217], v0 offset:0x2400
	ds_read_b64_tr_b16 v[218:219], v0 offset:0x2c00
	v_mfma_f32_32x32x16_bf16 v[50:65], v[204:207], v[220:223], v[50:65]
	ds_read_b64_tr_b16 v[220:221], v0 offset:0x3400
	ds_read_b64_tr_b16 v[222:223], v0 offset:0x3c00
	s_waitcnt lgkmcnt(0)
	v_mfma_f32_32x32x16_bf16 v[34:49], v[174:177], v[208:211], v[34:49]
	ds_read_b64_tr_b16 v[208:209], v0 offset:0x600
	ds_read_b64_tr_b16 v[210:211], v0 offset:0xe00
	v_mfma_f32_32x32x16_bf16 v[34:49], v[178:181], v[212:215], v[34:49]
	ds_read_b64_tr_b16 v[212:213], v0 offset:0x1600
	ds_read_b64_tr_b16 v[214:215], v0 offset:0x1e00
	v_mfma_f32_32x32x16_bf16 v[34:49], v[182:185], v[216:219], v[34:49]
	ds_read_b64_tr_b16 v[216:217], v0 offset:0x2600
	ds_read_b64_tr_b16 v[218:219], v0 offset:0x2e00
	v_mfma_f32_32x32x16_bf16 v[34:49], v[204:207], v[220:223], v[34:49]
	ds_read_b64_tr_b16 v[220:221], v0 offset:0x3600
	ds_read_b64_tr_b16 v[222:223], v0 offset:0x3e00
	s_waitcnt lgkmcnt(0)
	v_mfma_f32_32x32x16_bf16 v[18:33], v[174:177], v[208:211], v[18:33]
	v_max_f32_e32 v0, v83, v83
	v_max_f32_e32 v156, v82, v82
	v_max_f32_e32 v0, v156, v0
	v_max3_f32 v0, v0, v84, v85
	v_max3_f32 v0, v0, v86, v87
	v_max3_f32 v0, v0, v88, v89
	v_max3_f32 v0, v0, v90, v91
	v_max3_f32 v0, v0, v92, v93
	v_max3_f32 v0, v0, v94, v95
	v_mfma_f32_32x32x16_bf16 v[18:33], v[178:181], v[212:215], v[18:33]
	v_max3_f32 v0, v0, v96, v97
	v_max3_f32 v0, v0, v66, v67
	v_max3_f32 v0, v0, v68, v69
	v_max3_f32 v0, v0, v70, v71
	v_max3_f32 v0, v0, v72, v73
	v_max3_f32 v0, v0, v74, v75
	v_max3_f32 v0, v0, v76, v77
	v_max3_f32 v0, v0, v78, v79
	v_mfma_f32_32x32x16_bf16 v[18:33], v[182:185], v[216:219], v[18:33]
	v_max3_f32 v0, v0, v80, v81
	v_mov_b32_e32 v156, v0
	s_nop 1
	v_permlane32_swap_b32_e32 v0, v156
	v_max_f32_e32 v156, v156, v156
	v_max_f32_e32 v0, v0, v0
	v_max_f32_e32 v0, v0, v156
	v_sub_f32_e32 v156, v0, v202
	v_cmp_ge_f32_e32 vcc, s27, v156
	v_max_f32_e32 v156, v202, v202
	v_max_f32_e32 v0, v156, v0
	v_mfma_f32_32x32x16_bf16 v[18:33], v[204:207], v[220:223], v[18:33]
	v_sub_f32_e32 v156, v202, v0
	v_mul_f32_e32 v156, 0x3dd53b94, v156
	v_exp_f32_e32 v156, v156
	s_cmp_eq_u64 vcc, exec
	s_cselect_b64 s[0:1], -1, 0
	v_cndmask_b32_e64 v174, v156, 1.0, s[0:1]
	v_cmp_gt_f32_e32 vcc, 1.0, v174
	s_cbranch_vccz .LBB2_337
	s_and_saveexec_b64 s[2:3], s[36:37]
	ds_write_b32 v194, v174 offset:128
	s_or_b64 exec, exec, s[2:3]
	s_waitcnt lgkmcnt(0)
	v_add_u32_e32 v156, s60, v162
	ds_read_b128 v[176:179], v156 offset:224
	ds_read_b128 v[180:183], v156 offset:192
	ds_read_b128 v[184:187], v156 offset:160
	ds_read_b128 v[204:207], v156 offset:128
	s_waitcnt lgkmcnt(0)
	v_pk_mul_f32 v[14:15], v[14:15], v[176:177]
	v_pk_mul_f32 v[10:11], v[10:11], v[180:181]
	v_pk_mul_f32 v[6:7], v[6:7], v[184:185]
	v_pk_mul_f32 v[16:17], v[16:17], v[178:179]
	v_pk_mul_f32 v[12:13], v[12:13], v[182:183]
	v_pk_mul_f32 v[8:9], v[8:9], v[186:187]
	v_pk_mul_f32 v[4:5], v[4:5], v[206:207]
	v_pk_mul_f32 v[2:3], v[2:3], v[204:205]
	v_pk_mul_f32 v[62:63], v[62:63], v[176:177]
	v_pk_mul_f32 v[58:59], v[58:59], v[180:181]
	v_pk_mul_f32 v[54:55], v[54:55], v[184:185]
	v_pk_mul_f32 v[64:65], v[64:65], v[178:179]
	v_pk_mul_f32 v[60:61], v[60:61], v[182:183]
	v_pk_mul_f32 v[56:57], v[56:57], v[186:187]
	v_pk_mul_f32 v[52:53], v[52:53], v[206:207]
	v_pk_mul_f32 v[50:51], v[50:51], v[204:205]
	v_pk_mul_f32 v[46:47], v[46:47], v[176:177]
	v_pk_mul_f32 v[42:43], v[42:43], v[180:181]
	v_pk_mul_f32 v[38:39], v[38:39], v[184:185]
	v_pk_mul_f32 v[48:49], v[48:49], v[178:179]
	v_pk_mul_f32 v[44:45], v[44:45], v[182:183]
	v_pk_mul_f32 v[40:41], v[40:41], v[186:187]
	v_pk_mul_f32 v[36:37], v[36:37], v[206:207]
	v_pk_mul_f32 v[34:35], v[34:35], v[204:205]
	v_pk_mul_f32 v[30:31], v[30:31], v[176:177]
	v_pk_mul_f32 v[26:27], v[26:27], v[180:181]
	v_pk_mul_f32 v[22:23], v[22:23], v[184:185]
	v_pk_mul_f32 v[32:33], v[32:33], v[178:179]
	v_pk_mul_f32 v[28:29], v[28:29], v[182:183]
	v_pk_mul_f32 v[24:25], v[24:25], v[186:187]
	v_pk_mul_f32 v[20:21], v[20:21], v[206:207]
	v_pk_mul_f32 v[18:19], v[18:19], v[204:205]

.LBB2_339:
	s_add_i32 s2, s64, 1
	s_and_b32 s2, s2, 3
	s_add_i32 s3, s40, 1
	s_cmp_lg_u32 s40, 2
	s_cselect_b32 s25, s3, 0
	s_add_i32 s3, s24, 1
	s_cmp_lg_u32 s24, 2
	v_cndmask_b32_e64 v0, v0, v202, s[0:1]
	s_cselect_b32 s24, s3, 0
	v_mul_f32_e32 v180, 0xbdd53b94, v0
	s_mov_b64 s[0:1], 0xe860000
	v_fmamk_f32 v204, v66, 0x3dd53b94, v180
	v_fmamk_f32 v205, v67, 0x3dd53b94, v180
	v_lshl_add_u64 v[66:67], v[168:169], 0, s[0:1]
	s_lshl_b32 s0, s24, 14
	s_add_i32 s3, s62, s0
	s_mov_b32 m0, s3
	s_mov_b64 s[0:1], 0xe870000
	global_load_lds_dwordx4 v[66:67], off
	v_lshl_add_u64 v[66:67], v[168:169], 0, s[0:1]
	s_add_i32 m0, s3, 0x2000
	v_fmamk_f32 v90, v90, 0x3dd53b94, v180
	global_load_lds_dwordx4 v[66:67], off
	v_exp_f32_e32 v170, v90
	v_fmamk_f32 v82, v82, 0x3dd53b94, v180
	v_fmamk_f32 v83, v83, 0x3dd53b94, v180
	v_fmamk_f32 v84, v84, 0x3dd53b94, v180
	v_fmamk_f32 v85, v85, 0x3dd53b94, v180
	v_fmamk_f32 v86, v86, 0x3dd53b94, v180
	v_fmamk_f32 v87, v87, 0x3dd53b94, v180
	v_fmamk_f32 v88, v88, 0x3dd53b94, v180
	v_fmamk_f32 v89, v89, 0x3dd53b94, v180
	v_fmamk_f32 v91, v91, 0x3dd53b94, v180
	v_fmamk_f32 v92, v92, 0x3dd53b94, v180
	v_fmamk_f32 v93, v93, 0x3dd53b94, v180
	v_fmamk_f32 v94, v94, 0x3dd53b94, v180
	v_fmamk_f32 v95, v95, 0x3dd53b94, v180
	v_fmamk_f32 v96, v96, 0x3dd53b94, v180
	v_fmamk_f32 v97, v97, 0x3dd53b94, v180
	v_fmamk_f32 v206, v68, 0x3dd53b94, v180
	v_fmamk_f32 v207, v69, 0x3dd53b94, v180
	v_fmamk_f32 v208, v70, 0x3dd53b94, v180
	v_fmamk_f32 v209, v71, 0x3dd53b94, v180
	v_fmamk_f32 v210, v72, 0x3dd53b94, v180
	v_fmamk_f32 v211, v73, 0x3dd53b94, v180
	v_fmamk_f32 v212, v74, 0x3dd53b94, v180
	v_fmamk_f32 v213, v75, 0x3dd53b94, v180
	v_fmamk_f32 v214, v76, 0x3dd53b94, v180
	v_fmamk_f32 v215, v77, 0x3dd53b94, v180
	v_fmamk_f32 v216, v78, 0x3dd53b94, v180
	v_fmamk_f32 v217, v79, 0x3dd53b94, v180
	v_fmamk_f32 v218, v80, 0x3dd53b94, v180
	v_fmac_f32_e32 v180, 0x3dd53b94, v81
	v_exp_f32_e32 v182, v82
	v_exp_f32_e32 v183, v83
	v_exp_f32_e32 v184, v84
	v_exp_f32_e32 v185, v85
	v_exp_f32_e32 v186, v86
	v_exp_f32_e32 v187, v87
	v_exp_f32_e32 v202, v88
	v_exp_f32_e32 v203, v89
	v_exp_f32_e32 v171, v91
	v_exp_f32_e32 v175, v92
	v_exp_f32_e32 v176, v93
	v_exp_f32_e32 v177, v94
	v_exp_f32_e32 v178, v95
	v_exp_f32_e32 v179, v96
	v_exp_f32_e32 v181, v97
	s_mulk_i32 s2, 0x6000
	s_add_i32 s0, s2, 0
	v_add_u32_e32 v156, s0, v197
	v_add_u32_e32 v157, s0, v198
	v_add_u32_e32 v158, s0, v199
	ds_read_b128 v[66:69], v156 offset:0
	ds_read_b128 v[70:73], v156 offset:0x1000
	ds_read_b128 v[220:223], v157 offset:0
	ds_read_b128 v[224:227], v157 offset:0x1000
	ds_read_b128 v[228:231], v158 offset:0
	ds_read_b128 v[232:235], v158 offset:0x1000
	v_add_u32_e32 v159, s0, v200
	s_setprio 1
	s_waitcnt lgkmcnt(4)
	ds_read_b128 v[236:239], v159 offset:0
	ds_read_b128 v[240:243], v159 offset:0x1000
	s_waitcnt lgkmcnt(4)
	v_mfma_f32_32x32x16_bf16 v[82:97], v[66:69], v[142:145], 0
	v_mfma_f32_32x32x16_bf16 v[66:81], v[70:73], v[142:145], 0
	v_mfma_f32_32x32x16_bf16 v[82:97], v[220:223], v[138:141], v[82:97]
	ds_read_b128 v[220:223], v156 offset:0x2000
	v_mfma_f32_32x32x16_bf16 v[66:81], v[224:227], v[138:141], v[66:81]
	ds_read_b128 v[224:227], v156 offset:0x3000
	s_waitcnt lgkmcnt(4)
	v_mfma_f32_32x32x16_bf16 v[82:97], v[228:231], v[134:137], v[82:97]
	ds_read_b128 v[228:231], v157 offset:0x2000
	v_mfma_f32_32x32x16_bf16 v[66:81], v[232:235], v[134:137], v[66:81]
	ds_read_b128 v[232:235], v157 offset:0x3000
	s_waitcnt lgkmcnt(4)
	v_mfma_f32_32x32x16_bf16 v[82:97], v[236:239], v[130:133], v[82:97]
	ds_read_b128 v[236:239], v158 offset:0x2000
	v_mfma_f32_32x32x16_bf16 v[66:81], v[240:243], v[130:133], v[66:81]
	ds_read_b128 v[240:243], v158 offset:0x3000
	s_waitcnt lgkmcnt(4)
	v_mfma_f32_32x32x16_bf16 v[82:97], v[220:223], v[126:129], v[82:97]
	ds_read_b128 v[220:223], v159 offset:0x2000
	v_mfma_f32_32x32x16_bf16 v[66:81], v[224:227], v[126:129], v[66:81]
	ds_read_b128 v[224:227], v159 offset:0x3000
	s_waitcnt lgkmcnt(4)
	v_mfma_f32_32x32x16_bf16 v[82:97], v[228:231], v[122:125], v[82:97]
	ds_read_b128 v[228:231], v156 offset:0x4000
	v_mfma_f32_32x32x16_bf16 v[66:81], v[232:235], v[122:125], v[66:81]
	ds_read_b128 v[232:235], v156 offset:0x5000
	s_waitcnt lgkmcnt(4)
	v_mfma_f32_32x32x16_bf16 v[82:97], v[236:239], v[118:121], v[82:97]
	ds_read_b128 v[236:239], v157 offset:0x4000
	v_mfma_f32_32x32x16_bf16 v[66:81], v[240:243], v[118:121], v[66:81]
	ds_read_b128 v[240:243], v157 offset:0x5000
	s_waitcnt lgkmcnt(4)
	v_mfma_f32_32x32x16_bf16 v[82:97], v[220:223], v[114:117], v[82:97]
	ds_read_b128 v[220:223], v158 offset:0x4000
	v_mfma_f32_32x32x16_bf16 v[66:81], v[224:227], v[114:117], v[66:81]
	ds_read_b128 v[224:227], v158 offset:0x5000
	s_waitcnt lgkmcnt(4)
	v_mfma_f32_32x32x16_bf16 v[82:97], v[228:231], v[110:113], v[82:97]
	ds_read_b128 v[228:231], v159 offset:0x4000
	v_mfma_f32_32x32x16_bf16 v[66:81], v[232:235], v[110:113], v[66:81]
	ds_read_b128 v[232:235], v159 offset:0x5000
	s_waitcnt lgkmcnt(4)
	s_waitcnt lgkmcnt(2)
	s_nop 0
	s_waitcnt lgkmcnt(0)
	v_mfma_f32_32x32x16_bf16 v[82:97], v[236:239], v[106:109], v[82:97]
	v_mfma_f32_32x32x16_bf16 v[66:81], v[240:243], v[106:109], v[66:81]
	v_mfma_f32_32x32x16_bf16 v[82:97], v[220:223], v[102:105], v[82:97]
	v_mfma_f32_32x32x16_bf16 v[66:81], v[224:227], v[102:105], v[66:81]
	v_mfma_f32_32x32x16_bf16 v[82:97], v[228:231], v[98:101], v[82:97]
	v_mfma_f32_32x32x16_bf16 v[66:81], v[232:235], v[98:101], v[66:81]
	s_setprio 0
	v_add_f32_e32 v169, 0, v182
	v_add_f32_e32 v169, v183, v169
	v_add_f32_e32 v169, v184, v169
	v_add_f32_e32 v169, v185, v169
	v_add_f32_e32 v169, v186, v169
	v_add_f32_e32 v169, v187, v169
	v_add_f32_e32 v169, v202, v169
	v_add_f32_e32 v169, v203, v169
	v_add_f32_e32 v169, v170, v169
	v_add_f32_e32 v169, v171, v169
	v_add_f32_e32 v169, v175, v169
	v_add_f32_e32 v169, v176, v169
	v_exp_f32_e32 v156, v204
	v_add_f32_e32 v169, v177, v169
	v_exp_f32_e32 v157, v205
	v_add_f32_e32 v169, v178, v169
	v_exp_f32_e32 v158, v206
	v_add_f32_e32 v169, v179, v169
	v_exp_f32_e32 v159, v207
	v_add_f32_e32 v169, v181, v169
	v_exp_f32_e32 v168, v208
	v_add_f32_e32 v169, v156, v169
	v_exp_f32_e32 v206, v209
	v_add_f32_e32 v169, v157, v169
	v_exp_f32_e32 v207, v210
	v_add_f32_e32 v169, v158, v169
	v_exp_f32_e32 v208, v211
	v_add_f32_e32 v169, v159, v169
	v_exp_f32_e32 v209, v212
	v_add_f32_e32 v169, v168, v169
	v_exp_f32_e32 v210, v213
	v_add_f32_e32 v169, v206, v169
	v_exp_f32_e32 v211, v214
	v_add_f32_e32 v169, v207, v169
	v_exp_f32_e32 v212, v215
	v_add_f32_e32 v169, v208, v169
	v_exp_f32_e32 v213, v216
	v_add_f32_e32 v169, v209, v169
	v_exp_f32_e32 v214, v217
	v_add_f32_e32 v169, v210, v169
	v_exp_f32_e32 v215, v218
	v_add_f32_e32 v169, v211, v169
	v_exp_f32_e32 v216, v180
	v_add_f32_e32 v169, v212, v169
	v_add_f32_e32 v169, v213, v169
	v_add_f32_e32 v169, v214, v169
	v_add_f32_e32 v169, v215, v169
	v_add_f32_e32 v169, v216, v169
	v_mov_b32_e32 v180, v169
	s_nop 1
	v_permlane32_swap_b32_e32 v169, v180
	v_cvt_pk_bf16_f32 v182, v182, v183
	v_cvt_pk_bf16_f32 v183, v184, v185
	v_cvt_pk_bf16_f32 v184, v186, v187
	v_cvt_pk_bf16_f32 v185, v202, v203
	v_cvt_pk_bf16_f32 v202, v170, v171
	v_cvt_pk_bf16_f32 v203, v175, v176
	v_cvt_pk_bf16_f32 v204, v177, v178
	v_cvt_pk_bf16_f32 v205, v179, v181
	v_cvt_pk_bf16_f32 v176, v156, v157
	v_cvt_pk_bf16_f32 v177, v158, v159
	v_cvt_pk_bf16_f32 v178, v168, v206
	v_cvt_pk_bf16_f32 v179, v207, v208
	v_cvt_pk_bf16_f32 v206, v209, v210
	v_cvt_pk_bf16_f32 v207, v211, v212
	v_cvt_pk_bf16_f32 v208, v213, v214
	v_cvt_pk_bf16_f32 v209, v215, v216
	s_nop 0
	v_permlane32_swap_b32_e32 v182, v184
	v_permlane32_swap_b32_e32 v183, v185
	v_permlane32_swap_b32_e32 v202, v204
	v_permlane32_swap_b32_e32 v203, v205
	v_permlane32_swap_b32_e32 v176, v178
	v_permlane32_swap_b32_e32 v177, v179
	v_permlane32_swap_b32_e32 v206, v208
	v_permlane32_swap_b32_e32 v207, v209
	v_lshl_add_u32 v156, s25, 14, v196
	ds_read_b64_tr_b16 v[210:211], v156 offset:0
	ds_read_b64_tr_b16 v[212:213], v156 offset:0x800
	ds_read_b64_tr_b16 v[214:215], v156 offset:0x1000
	ds_read_b64_tr_b16 v[216:217], v156 offset:0x1800
	ds_read_b64_tr_b16 v[218:219], v156 offset:0x2000
	ds_read_b64_tr_b16 v[220:221], v156 offset:0x2800
	ds_read_b64_tr_b16 v[222:223], v156 offset:0x3000
	ds_read_b64_tr_b16 v[224:225], v156 offset:0x3800
	s_waitcnt lgkmcnt(0)
	s_nop 0
	v_mfma_f32_32x32x16_bf16 v[2:17], v[182:185], v[210:213], v[2:17]
	ds_read_b64_tr_b16 v[210:211], v156 offset:0x200
	ds_read_b64_tr_b16 v[212:213], v156 offset:0xa00
	v_mfma_f32_32x32x16_bf16 v[2:17], v[202:205], v[214:217], v[2:17]
	ds_read_b64_tr_b16 v[214:215], v156 offset:0x1200
	ds_read_b64_tr_b16 v[216:217], v156 offset:0x1a00
	v_mfma_f32_32x32x16_bf16 v[2:17], v[176:179], v[218:221], v[2:17]
	ds_read_b64_tr_b16 v[218:219], v156 offset:0x2200
	ds_read_b64_tr_b16 v[220:221], v156 offset:0x2a00
	v_mfma_f32_32x32x16_bf16 v[2:17], v[206:209], v[222:225], v[2:17]
	ds_read_b64_tr_b16 v[222:223], v156 offset:0x3200
	ds_read_b64_tr_b16 v[224:225], v156 offset:0x3a00
	s_waitcnt lgkmcnt(0)
	v_mfma_f32_32x32x16_bf16 v[50:65], v[182:185], v[210:213], v[50:65]
	ds_read_b64_tr_b16 v[210:211], v156 offset:0x400
	ds_read_b64_tr_b16 v[212:213], v156 offset:0xc00
	v_mfma_f32_32x32x16_bf16 v[50:65], v[202:205], v[214:217], v[50:65]
	ds_read_b64_tr_b16 v[214:215], v156 offset:0x1400
	ds_read_b64_tr_b16 v[216:217], v156 offset:0x1c00
	v_mfma_f32_32x32x16_bf16 v[50:65], v[176:179], v[218:221], v[50:65]
	ds_read_b64_tr_b16 v[218:219], v156 offset:0x2400
	ds_read_b64_tr_b16 v[220:221], v156 offset:0x2c00
	v_mfma_f32_32x32x16_bf16 v[50:65], v[206:209], v[222:225], v[50:65]
	ds_read_b64_tr_b16 v[222:223], v156 offset:0x3400
	ds_read_b64_tr_b16 v[224:225], v156 offset:0x3c00
	s_waitcnt lgkmcnt(0)
	v_mfma_f32_32x32x16_bf16 v[34:49], v[182:185], v[210:213], v[34:49]
	ds_read_b64_tr_b16 v[210:211], v156 offset:0x600
	ds_read_b64_tr_b16 v[212:213], v156 offset:0xe00
	v_mfma_f32_32x32x16_bf16 v[34:49], v[202:205], v[214:217], v[34:49]
	ds_read_b64_tr_b16 v[214:215], v156 offset:0x1600
	ds_read_b64_tr_b16 v[216:217], v156 offset:0x1e00
	v_mfma_f32_32x32x16_bf16 v[34:49], v[176:179], v[218:221], v[34:49]
	ds_read_b64_tr_b16 v[218:219], v156 offset:0x2600
	ds_read_b64_tr_b16 v[220:221], v156 offset:0x2e00
	v_mfma_f32_32x32x16_bf16 v[34:49], v[206:209], v[222:225], v[34:49]
	ds_read_b64_tr_b16 v[222:223], v156 offset:0x3600
	ds_read_b64_tr_b16 v[224:225], v156 offset:0x3e00
	s_waitcnt lgkmcnt(0)
	v_mfma_f32_32x32x16_bf16 v[18:33], v[182:185], v[210:213], v[18:33]
	v_max_f32_e32 v156, v83, v83
	v_max_f32_e32 v157, v82, v82
	v_max_f32_e32 v156, v157, v156
	v_max3_f32 v156, v156, v84, v85
	v_max3_f32 v156, v156, v86, v87
	v_max3_f32 v156, v156, v88, v89
	v_max3_f32 v156, v156, v90, v91
	v_max3_f32 v156, v156, v92, v93
	v_max3_f32 v156, v156, v94, v95
	v_mfma_f32_32x32x16_bf16 v[18:33], v[202:205], v[214:217], v[18:33]
	v_max3_f32 v156, v156, v96, v97
	v_max3_f32 v156, v156, v66, v67
	v_max3_f32 v156, v156, v68, v69
	v_max3_f32 v156, v156, v70, v71
	v_max3_f32 v156, v156, v72, v73
	v_max3_f32 v156, v156, v74, v75
	v_max3_f32 v156, v156, v76, v77
	v_max3_f32 v156, v156, v78, v79
	v_mfma_f32_32x32x16_bf16 v[18:33], v[176:179], v[218:221], v[18:33]
	v_max3_f32 v156, v156, v80, v81
	v_mov_b32_e32 v157, v156
	s_nop 1
	v_permlane32_swap_b32_e32 v156, v157
	v_max_f32_e32 v157, v157, v157
	v_max_f32_e32 v156, v156, v156
	v_max_f32_e32 v156, v156, v157
	v_sub_f32_e32 v157, v156, v0
	v_cmp_ge_f32_e32 vcc, s27, v157
	v_max_f32_e32 v157, v0, v0
	v_max_f32_e32 v170, v157, v156
	v_mfma_f32_32x32x16_bf16 v[18:33], v[206:209], v[222:225], v[18:33]
	v_sub_f32_e32 v156, v0, v170
	v_mul_f32_e32 v156, 0x3dd53b94, v156
	v_exp_f32_e32 v156, v156
	s_cmp_eq_u64 vcc, exec
	s_cselect_b64 s[0:1], -1, 0
	v_cndmask_b32_e64 v168, v156, 1.0, s[0:1]
	v_cmp_gt_f32_e32 vcc, 1.0, v168
	s_cbranch_vccz .LBB2_343
	s_and_saveexec_b64 s[2:3], s[36:37]
	ds_write_b32 v194, v168 offset:128
	s_or_b64 exec, exec, s[2:3]
	s_waitcnt lgkmcnt(0)
	v_add_u32_e32 v156, s60, v162
	ds_read_b128 v[176:179], v156 offset:224
	ds_read_b128 v[182:185], v156 offset:192
	ds_read_b128 v[202:205], v156 offset:160
	ds_read_b128 v[206:209], v156 offset:128
	s_waitcnt lgkmcnt(0)
	v_pk_mul_f32 v[14:15], v[14:15], v[176:177]
	v_pk_mul_f32 v[10:11], v[10:11], v[182:183]
	v_pk_mul_f32 v[6:7], v[6:7], v[202:203]
	v_pk_mul_f32 v[16:17], v[16:17], v[178:179]
	v_pk_mul_f32 v[12:13], v[12:13], v[184:185]
	v_pk_mul_f32 v[8:9], v[8:9], v[204:205]
	v_pk_mul_f32 v[4:5], v[4:5], v[208:209]
	v_pk_mul_f32 v[2:3], v[2:3], v[206:207]
	v_pk_mul_f32 v[62:63], v[62:63], v[176:177]
	v_pk_mul_f32 v[58:59], v[58:59], v[182:183]
	v_pk_mul_f32 v[54:55], v[54:55], v[202:203]
	v_pk_mul_f32 v[64:65], v[64:65], v[178:179]
	v_pk_mul_f32 v[60:61], v[60:61], v[184:185]
	v_pk_mul_f32 v[56:57], v[56:57], v[204:205]
	v_pk_mul_f32 v[52:53], v[52:53], v[208:209]
	v_pk_mul_f32 v[50:51], v[50:51], v[206:207]
	v_pk_mul_f32 v[46:47], v[46:47], v[176:177]
	v_pk_mul_f32 v[42:43], v[42:43], v[182:183]
	v_pk_mul_f32 v[38:39], v[38:39], v[202:203]
	v_pk_mul_f32 v[48:49], v[48:49], v[178:179]
	v_pk_mul_f32 v[44:45], v[44:45], v[184:185]
	v_pk_mul_f32 v[40:41], v[40:41], v[204:205]
	v_pk_mul_f32 v[36:37], v[36:37], v[208:209]
	v_pk_mul_f32 v[34:35], v[34:35], v[206:207]
	v_pk_mul_f32 v[30:31], v[30:31], v[176:177]
	v_pk_mul_f32 v[26:27], v[26:27], v[182:183]
	v_pk_mul_f32 v[22:23], v[22:23], v[202:203]
	v_pk_mul_f32 v[32:33], v[32:33], v[178:179]
	v_pk_mul_f32 v[28:29], v[28:29], v[184:185]
	v_pk_mul_f32 v[24:25], v[24:25], v[204:205]
	v_pk_mul_f32 v[20:21], v[20:21], v[208:209]
	v_pk_mul_f32 v[18:19], v[18:19], v[206:207]

.LBB2_349:
	s_add_i32 s0, 0, 0x12000
	v_add_u32_e32 v0, s0, v197
	v_add_u32_e32 v156, s0, v198
	v_add_u32_e32 v157, s0, v199
	v_add_u32_e32 v158, s0, v200
	ds_read_b128 v[66:69], v0 offset:0
	ds_read_b128 v[70:73], v0 offset:0x1000
	ds_read_b128 v[164:167], v156 offset:0
	ds_read_b128 v[198:201], v156 offset:0x1000
	ds_read_b128 v[220:223], v157 offset:0
	ds_read_b128 v[224:227], v157 offset:0x1000
	s_setprio 1
	s_waitcnt lgkmcnt(4)
	v_mfma_f32_32x32x16_bf16 v[82:97], v[66:69], v[142:145], 0
	v_mfma_f32_32x32x16_bf16 v[66:81], v[70:73], v[142:145], 0
	ds_read_b128 v[142:145], v158 offset:0
	ds_read_b128 v[228:231], v158 offset:0x1000
	s_waitcnt lgkmcnt(4)
	v_mfma_f32_32x32x16_bf16 v[82:97], v[164:167], v[138:141], v[82:97]
	v_mfma_f32_32x32x16_bf16 v[66:81], v[198:201], v[138:141], v[66:81]
	ds_read_b128 v[138:141], v0 offset:0x2000
	ds_read_b128 v[164:167], v0 offset:0x3000
	s_waitcnt lgkmcnt(4)
	v_mfma_f32_32x32x16_bf16 v[82:97], v[220:223], v[134:137], v[82:97]
	v_mfma_f32_32x32x16_bf16 v[66:81], v[224:227], v[134:137], v[66:81]
	ds_read_b128 v[134:137], v156 offset:0x2000
	ds_read_b128 v[198:201], v156 offset:0x3000
	s_waitcnt lgkmcnt(4)
	v_mfma_f32_32x32x16_bf16 v[82:97], v[142:145], v[130:133], v[82:97]
	v_mfma_f32_32x32x16_bf16 v[66:81], v[228:231], v[130:133], v[66:81]
	ds_read_b128 v[130:133], v157 offset:0x2000
	ds_read_b128 v[142:145], v157 offset:0x3000
	s_waitcnt lgkmcnt(4)
	v_mfma_f32_32x32x16_bf16 v[82:97], v[138:141], v[126:129], v[82:97]
	v_mfma_f32_32x32x16_bf16 v[66:81], v[164:167], v[126:129], v[66:81]
	ds_read_b128 v[126:129], v158 offset:0x2000
	ds_read_b128 v[138:141], v158 offset:0x3000
	s_waitcnt lgkmcnt(4)
	v_mfma_f32_32x32x16_bf16 v[82:97], v[134:137], v[122:125], v[82:97]
	v_mfma_f32_32x32x16_bf16 v[66:81], v[198:201], v[122:125], v[66:81]
	ds_read_b128 v[122:125], v0 offset:0x4000
	ds_read_b128 v[134:137], v0 offset:0x5000
	s_waitcnt lgkmcnt(4)
	v_mfma_f32_32x32x16_bf16 v[82:97], v[130:133], v[118:121], v[82:97]
	v_mfma_f32_32x32x16_bf16 v[66:81], v[142:145], v[118:121], v[66:81]
	ds_read_b128 v[118:121], v156 offset:0x4000
	ds_read_b128 v[130:133], v156 offset:0x5000
	s_waitcnt lgkmcnt(4)
	v_mfma_f32_32x32x16_bf16 v[82:97], v[126:129], v[114:117], v[82:97]
	v_mfma_f32_32x32x16_bf16 v[66:81], v[138:141], v[114:117], v[66:81]
	ds_read_b128 v[114:117], v157 offset:0x4000
	ds_read_b128 v[126:129], v157 offset:0x5000
	s_waitcnt lgkmcnt(4)
	v_mfma_f32_32x32x16_bf16 v[82:97], v[122:125], v[110:113], v[82:97]
	v_mfma_f32_32x32x16_bf16 v[66:81], v[134:137], v[110:113], v[66:81]
	ds_read_b128 v[110:113], v158 offset:0x4000
	ds_read_b128 v[122:125], v158 offset:0x5000
	s_waitcnt lgkmcnt(4)
	s_waitcnt lgkmcnt(2)
	s_nop 0
	s_waitcnt lgkmcnt(0)
	v_mfma_f32_32x32x16_bf16 v[82:97], v[118:121], v[106:109], v[82:97]
	v_mfma_f32_32x32x16_bf16 v[66:81], v[130:133], v[106:109], v[66:81]
	v_mfma_f32_32x32x16_bf16 v[82:97], v[114:117], v[102:105], v[82:97]
	v_mfma_f32_32x32x16_bf16 v[66:81], v[126:129], v[102:105], v[66:81]
	v_mfma_f32_32x32x16_bf16 v[82:97], v[110:113], v[98:101], v[82:97]
	v_mfma_f32_32x32x16_bf16 v[66:81], v[122:125], v[98:101], v[66:81]
	s_setprio 0
	v_add_f32_e32 v0, 0, v216
	v_add_f32_e32 v0, v218, v0
	v_add_f32_e32 v0, v214, v0
	v_add_f32_e32 v0, v217, v0
	v_add_f32_e32 v0, v212, v0
	v_add_f32_e32 v0, v215, v0
	v_add_f32_e32 v0, v211, v0
	v_add_f32_e32 v0, v213, v0
	v_add_f32_e32 v0, v208, v0
	v_add_f32_e32 v0, v210, v0
	v_add_f32_e32 v0, v206, v0
	v_add_f32_e32 v0, v209, v0
	v_exp_f32_e32 v99, v186
	v_add_f32_e32 v0, v204, v0
	v_exp_f32_e32 v108, v187
	v_add_f32_e32 v0, v207, v0
	v_exp_f32_e32 v109, v184
	v_add_f32_e32 v0, v203, v0
	v_exp_f32_e32 v110, v185
	v_add_f32_e32 v0, v205, v0
	v_exp_f32_e32 v111, v182
	v_add_f32_e32 v0, v99, v0
	v_exp_f32_e32 v112, v183
	v_add_f32_e32 v0, v108, v0
	v_exp_f32_e32 v113, v180
	v_add_f32_e32 v0, v109, v0
	v_exp_f32_e32 v114, v181
	v_add_f32_e32 v0, v110, v0
	v_exp_f32_e32 v115, v178
	v_add_f32_e32 v0, v111, v0
	v_exp_f32_e32 v116, v179
	v_add_f32_e32 v0, v112, v0
	v_exp_f32_e32 v117, v176
	v_add_f32_e32 v0, v113, v0
	v_exp_f32_e32 v118, v177
	v_add_f32_e32 v0, v114, v0
	v_exp_f32_e32 v119, v174
	v_add_f32_e32 v0, v115, v0
	v_exp_f32_e32 v120, v175
	v_add_f32_e32 v0, v116, v0
	v_exp_f32_e32 v121, v172
	v_add_f32_e32 v0, v117, v0
	v_exp_f32_e32 v122, v173
	v_add_f32_e32 v0, v118, v0
	v_add_f32_e32 v0, v119, v0
	v_add_f32_e32 v0, v120, v0
	v_add_f32_e32 v0, v121, v0
	v_add_f32_e32 v0, v122, v0
	v_mov_b32_e32 v98, v0
	v_cvt_pk_bf16_f32 v100, v216, v218
	v_cvt_pk_bf16_f32 v101, v214, v217
	v_cvt_pk_bf16_f32 v102, v212, v215
	s_nop 1
	v_permlane32_swap_b32_e32 v0, v98
	v_cvt_pk_bf16_f32 v103, v211, v213
	v_permlane32_swap_b32_e32 v100, v102
	v_cvt_pk_bf16_f32 v104, v208, v210
	v_cvt_pk_bf16_f32 v105, v206, v209
	v_cvt_pk_bf16_f32 v106, v204, v207
	v_cvt_pk_bf16_f32 v107, v203, v205
	v_cvt_pk_bf16_f32 v108, v99, v108
	v_cvt_pk_bf16_f32 v109, v109, v110
	v_cvt_pk_bf16_f32 v110, v111, v112
	v_cvt_pk_bf16_f32 v111, v113, v114
	v_cvt_pk_bf16_f32 v112, v115, v116
	v_cvt_pk_bf16_f32 v113, v117, v118
	v_cvt_pk_bf16_f32 v114, v119, v120
	v_cvt_pk_bf16_f32 v115, v121, v122
	v_permlane32_swap_b32_e32 v101, v103
	v_permlane32_swap_b32_e32 v104, v106
	v_permlane32_swap_b32_e32 v105, v107
	v_permlane32_swap_b32_e32 v108, v110
	v_permlane32_swap_b32_e32 v109, v111
	v_permlane32_swap_b32_e32 v112, v114
	v_permlane32_swap_b32_e32 v113, v115
	ds_read_b64_tr_b16 v[116:117], v196 offset:0
	ds_read_b64_tr_b16 v[118:119], v196 offset:0x800
	ds_read_b64_tr_b16 v[120:121], v196 offset:0x1000
	ds_read_b64_tr_b16 v[122:123], v196 offset:0x1800
	ds_read_b64_tr_b16 v[124:125], v196 offset:0x2000
	ds_read_b64_tr_b16 v[126:127], v196 offset:0x2800
	ds_read_b64_tr_b16 v[128:129], v196 offset:0x3000
	ds_read_b64_tr_b16 v[130:131], v196 offset:0x3800
	s_waitcnt lgkmcnt(0)
	s_nop 0
	v_mfma_f32_32x32x16_bf16 v[2:17], v[100:103], v[116:119], v[2:17]
	ds_read_b64_tr_b16 v[116:117], v196 offset:0x200
	ds_read_b64_tr_b16 v[118:119], v196 offset:0xa00
	v_mfma_f32_32x32x16_bf16 v[2:17], v[104:107], v[120:123], v[2:17]
	ds_read_b64_tr_b16 v[120:121], v196 offset:0x1200
	ds_read_b64_tr_b16 v[122:123], v196 offset:0x1a00
	v_mfma_f32_32x32x16_bf16 v[2:17], v[108:111], v[124:127], v[2:17]
	ds_read_b64_tr_b16 v[124:125], v196 offset:0x2200
	ds_read_b64_tr_b16 v[126:127], v196 offset:0x2a00
	v_mfma_f32_32x32x16_bf16 v[2:17], v[112:115], v[128:131], v[2:17]
	ds_read_b64_tr_b16 v[128:129], v196 offset:0x3200
	ds_read_b64_tr_b16 v[130:131], v196 offset:0x3a00
	s_waitcnt lgkmcnt(0)
	v_mfma_f32_32x32x16_bf16 v[50:65], v[100:103], v[116:119], v[50:65]
	ds_read_b64_tr_b16 v[116:117], v196 offset:0x400
	ds_read_b64_tr_b16 v[118:119], v196 offset:0xc00
	v_mfma_f32_32x32x16_bf16 v[50:65], v[104:107], v[120:123], v[50:65]
	ds_read_b64_tr_b16 v[120:121], v196 offset:0x1400
	ds_read_b64_tr_b16 v[122:123], v196 offset:0x1c00
	v_mfma_f32_32x32x16_bf16 v[50:65], v[108:111], v[124:127], v[50:65]
	ds_read_b64_tr_b16 v[124:125], v196 offset:0x2400
	ds_read_b64_tr_b16 v[126:127], v196 offset:0x2c00
	v_mfma_f32_32x32x16_bf16 v[50:65], v[112:115], v[128:131], v[50:65]
	ds_read_b64_tr_b16 v[128:129], v196 offset:0x3400
	ds_read_b64_tr_b16 v[130:131], v196 offset:0x3c00
	s_waitcnt lgkmcnt(0)
	v_mfma_f32_32x32x16_bf16 v[34:49], v[100:103], v[116:119], v[34:49]
	ds_read_b64_tr_b16 v[116:117], v196 offset:0x600
	ds_read_b64_tr_b16 v[118:119], v196 offset:0xe00
	v_mfma_f32_32x32x16_bf16 v[34:49], v[104:107], v[120:123], v[34:49]
	ds_read_b64_tr_b16 v[120:121], v196 offset:0x1600
	ds_read_b64_tr_b16 v[122:123], v196 offset:0x1e00
	v_mfma_f32_32x32x16_bf16 v[34:49], v[108:111], v[124:127], v[34:49]
	ds_read_b64_tr_b16 v[124:125], v196 offset:0x2600
	ds_read_b64_tr_b16 v[126:127], v196 offset:0x2e00
	v_mfma_f32_32x32x16_bf16 v[34:49], v[112:115], v[128:131], v[34:49]
	ds_read_b64_tr_b16 v[128:129], v196 offset:0x3600
	ds_read_b64_tr_b16 v[130:131], v196 offset:0x3e00
	s_waitcnt lgkmcnt(0)
	v_mfma_f32_32x32x16_bf16 v[18:33], v[100:103], v[116:119], v[18:33]
	v_max_f32_e32 v99, v83, v83
	v_max_f32_e32 v100, v82, v82
	v_max_f32_e32 v99, v100, v99
	v_max3_f32 v99, v99, v84, v85
	v_max3_f32 v99, v99, v86, v87
	v_max3_f32 v99, v99, v88, v89
	v_max3_f32 v99, v99, v90, v91
	v_max3_f32 v99, v99, v92, v93
	v_max3_f32 v99, v99, v94, v95
	v_mfma_f32_32x32x16_bf16 v[18:33], v[104:107], v[120:123], v[18:33]
	v_max3_f32 v99, v99, v96, v97
	v_max3_f32 v99, v99, v66, v67
	v_max3_f32 v99, v99, v68, v69
	v_max3_f32 v99, v99, v70, v71
	v_max3_f32 v99, v99, v72, v73
	v_max3_f32 v99, v99, v74, v75
	v_max3_f32 v99, v99, v76, v77
	v_max3_f32 v99, v99, v78, v79
	v_mfma_f32_32x32x16_bf16 v[18:33], v[108:111], v[124:127], v[18:33]
	v_max3_f32 v99, v99, v80, v81
	v_mov_b32_e32 v100, v99
	s_nop 1
	v_permlane32_swap_b32_e32 v99, v100
	v_max_f32_e32 v100, v100, v100
	v_max_f32_e32 v99, v99, v99
	v_max_f32_e32 v99, v99, v100
	v_sub_f32_e32 v100, v99, v202
	v_cmp_ge_f32_e32 vcc, s27, v100
	v_max_f32_e32 v100, v202, v202
	v_max_f32_e32 v100, v100, v99
	v_mfma_f32_32x32x16_bf16 v[18:33], v[112:115], v[128:131], v[18:33]
	v_sub_f32_e32 v99, v202, v100
	v_mul_f32_e32 v99, 0x3dd53b94, v99
	v_exp_f32_e32 v99, v99
	s_cmp_eq_u64 vcc, exec
	s_cselect_b64 s[0:1], -1, 0
	v_cndmask_b32_e64 v99, v99, 1.0, s[0:1]
	v_cmp_gt_f32_e32 vcc, 1.0, v99
	s_cbranch_vccz .LBB2_353
	s_and_saveexec_b64 s[2:3], s[36:37]
	ds_write_b32 v194, v99 offset:128
	s_or_b64 exec, exec, s[2:3]
	s_waitcnt lgkmcnt(0)
	v_add_u32_e32 v101, s60, v162
	ds_read_b128 v[102:105], v101 offset:224
	ds_read_b128 v[106:109], v101 offset:192
	ds_read_b128 v[110:113], v101 offset:160
	ds_read_b128 v[114:117], v101 offset:128
	s_waitcnt lgkmcnt(0)
	v_pk_mul_f32 v[14:15], v[14:15], v[102:103]
	v_pk_mul_f32 v[10:11], v[10:11], v[106:107]
	v_pk_mul_f32 v[6:7], v[6:7], v[110:111]
	v_pk_mul_f32 v[16:17], v[16:17], v[104:105]
	v_pk_mul_f32 v[12:13], v[12:13], v[108:109]
	v_pk_mul_f32 v[8:9], v[8:9], v[112:113]
	v_pk_mul_f32 v[4:5], v[4:5], v[116:117]
	v_pk_mul_f32 v[2:3], v[2:3], v[114:115]
	v_pk_mul_f32 v[62:63], v[62:63], v[102:103]
	v_pk_mul_f32 v[58:59], v[58:59], v[106:107]
	v_pk_mul_f32 v[54:55], v[54:55], v[110:111]
	v_pk_mul_f32 v[64:65], v[64:65], v[104:105]
	v_pk_mul_f32 v[60:61], v[60:61], v[108:109]
	v_pk_mul_f32 v[56:57], v[56:57], v[112:113]
	v_pk_mul_f32 v[52:53], v[52:53], v[116:117]
	v_pk_mul_f32 v[50:51], v[50:51], v[114:115]
	v_pk_mul_f32 v[46:47], v[46:47], v[102:103]
	v_pk_mul_f32 v[42:43], v[42:43], v[106:107]
	v_pk_mul_f32 v[38:39], v[38:39], v[110:111]
	v_pk_mul_f32 v[48:49], v[48:49], v[104:105]
	v_pk_mul_f32 v[44:45], v[44:45], v[108:109]
	v_pk_mul_f32 v[40:41], v[40:41], v[112:113]
	v_pk_mul_f32 v[36:37], v[36:37], v[116:117]
	v_pk_mul_f32 v[34:35], v[34:35], v[114:115]
	v_pk_mul_f32 v[30:31], v[30:31], v[102:103]
	v_pk_mul_f32 v[26:27], v[26:27], v[106:107]
	v_pk_mul_f32 v[22:23], v[22:23], v[110:111]
	v_pk_mul_f32 v[32:33], v[32:33], v[104:105]
	v_pk_mul_f32 v[28:29], v[28:29], v[108:109]
	v_pk_mul_f32 v[24:25], v[24:25], v[112:113]
	v_pk_mul_f32 v[20:21], v[20:21], v[116:117]
	v_pk_mul_f32 v[18:19], v[18:19], v[114:115]
